# attention tile loads through per-wave SGPR bases + two 32-bit lane offsets (drops the 64-bit VALU address arithmetic from the MFMA half)
# baseline (speedup 1.0000x reference)
.LBB0_227:
	s_lshl_b32 s4, s59, 11
	s_and_b32 s5, s4, 0x1000000
	s_lshl_b32 s4, s36, 4
	s_and_b32 s28, s4, 0x700
	v_lshl_or_b32 v96, v148, 1, s28
	v_or_b32_e32 v96, s5, v96
	v_mov_b32_e32 v97, v209
	s_lshl_b32 s21, s21, 9
	s_mov_b32 s65, 2
	s_add_i32 s66, s8, 2
	s_mov_b32 s4, 1
	v_lshl_add_u64 v[174:175], v[170:171], 0, v[96:97]
	v_subrev_u32_e32 v204, s21, v194
	s_add_i32 s33, s61, s8
	s_mov_b32 s87, 0
	s_movk_i32 s68, 0xff00
	v_readfirstlane_b32 s80, v174
	v_readfirstlane_b32 s81, v175
	s_nop 1
	v_subrev_u32_e32 v232, s80, v174
	v_add_u32_e32 v233, 0x10000, v232
	s_add_u32 s92, s80, 0xf5ff0000
	s_addc_u32 s93, s81, -1
	s_add_u32 s80, s80, 0xffff0000
	s_addc_u32 s81, s81, -1
	s_waitcnt lgkmcnt(0)
	s_barrier
	s_and_b64 vcc, exec, s[16:17]
	s_cbranch_vccnz .LBB0_228
	s_mov_b32 s5, 0
	s_mov_b32 s28, 0xa000
	s_cmp_ge_u32 s65, s66
	s_cbranch_scc1 .Latt_p_qk
	v_add_u32_e32 v176, s5, v157
	s_waitcnt vmcnt(3)
	ds_write_b128 v176, v[128:131]
	v_add_u32_e32 v176, s28, v159
	s_waitcnt vmcnt(2)
	ds_write_b128 v176, v[132:135] offset:34816
	v_add_u32_e32 v176, s5, v161
	s_waitcnt vmcnt(1)
	ds_write_b128 v176, v[136:139]
	v_add_u32_e32 v176, s28, v163
	s_cmp_lt_u32 s8, 2
	s_waitcnt vmcnt(0)
	ds_write_b128 v176, v[140:143] offset:34816
	s_cbranch_scc1 .Latt_p_shift
	global_load_dwordx4 v[128:131], v232, s[92:93]
	global_load_dwordx4 v[132:135], v232, s[80:81]
	global_load_dwordx4 v[136:139], v233, s[92:93]
	global_load_dwordx4 v[140:143], v233, s[80:81]
.Latt_p_shift:
	s_add_u32 s80, s80, 0x20000
	s_addc_u32 s81, s81, 0
	s_add_u32 s92, s92, 0x20000
	s_addc_u32 s93, s93, 0

.Latt_b_stg:
	s_mul_i32 s29, s87, 0x5000
	s_add_i32 s28, s65, 1
	s_cmp_ge_u32 s28, s66
	s_cbranch_scc1 .LBB0_241
	v_add_u32_e32 v176, s5, v157
	s_waitcnt vmcnt(3)
	ds_write_b128 v176, v[128:131]
	v_add_u32_e32 v176, s29, v159
	s_waitcnt vmcnt(2)
	ds_write_b128 v176, v[132:135] offset:34816
	v_add_u32_e32 v176, s5, v161
	s_waitcnt vmcnt(1)
	ds_write_b128 v176, v[136:139]
	v_add_u32_e32 v176, s29, v163
	s_add_i32 s28, s86, 1
	s_cmp_ge_u32 s28, s8
	s_waitcnt vmcnt(0)
	ds_write_b128 v176, v[140:143] offset:34816
	s_cbranch_scc1 .LBB0_241
	global_load_dwordx4 v[128:131], v232, s[92:93]
	global_load_dwordx4 v[132:135], v232, s[80:81]
	global_load_dwordx4 v[136:139], v233, s[92:93]
	global_load_dwordx4 v[140:143], v233, s[80:81]
	s_branch .LBB0_241
